# 10 XCD-local seams; the two write-after-read seams as split arrive/wait barriers a phase apart; only 2 full grid barriers remain
# speedup vs baseline: 1.0484x; 1.0086x over previous
; DI unsigned xb_ld(unsigned* p) { return __hip_atomic_load(p, __ATOMIC_RELAXED, __HIP_MEMORY_SCOPE_AGENT); }
; DI unsigned xb_add(unsigned* p, unsigned v) { return __hip_atomic_fetch_add(p, v, __ATOMIC_RELAXED, __HIP_MEMORY_SCOPE_AGENT); }
; #define XB_SPIN(cond, bar) do { unsigned _sp = 0; while (cond) { __builtin_amdgcn_s_sleep(1); \
;     if ((++_sp & 255u) == 0u) { if (xb_ld(&(bar)[XB_TMO])) break; if (_sp > XB_SPIN_CAP) { atomicAdd(&(bar)[XB_TMO], 1u); break; } } } } while (0)
; DI void xcd_barrier(const XcdBarrier& b) {
;     ...
;     if (old + 1u == (gen + 1u) * nloc) {
;       __builtin_amdgcn_fence(__ATOMIC_RELEASE, "agent");
;       asm volatile("s_waitcnt vmcnt(0)" ::: "memory");
;       const unsigned og = xb_add(&bar[XB_TOP], 1u);
;       const unsigned tg = og / nx;
;       if (og + 1u == (tg + 1u) * nx) xb_add(&bar[XB_TOPGEN], 1u);
;       else XB_SPIN(xb_ld(&bar[XB_TOPGEN]) == tg, bar);
.LBB0_532:
	s_andn2_saveexec_b64 s[2:3], s[6:7]
	s_cbranch_execz .LBB0_552
	s_mov_b64 s[6:7], exec
	v_mov_b32_e32 v255, 0
	ds_read_b32 v255, v255 offset:264
	s_waitcnt lgkmcnt(0)
	v_cmp_ne_u32_e32 vcc, 0, v255
	s_cbranch_vccz .Lxl_full_3
	v_mov_b32_e32 v255, 0xbfa0208
	v_mov_b32_e32 v0, 1
	global_atomic_add v255, v0, s[86:87]
	s_branch .LBB0_549
.Lxl_full_3:
	buffer_wbl2 sc1
	s_waitcnt lgkmcnt(0)
	s_waitcnt vmcnt(0)
	v_mbcnt_lo_u32_b32 v0, s6, 0
	v_mbcnt_hi_u32_b32 v0, s7, v0
	v_cmp_eq_u32_e32 vcc, 0, v0
	s_and_saveexec_b64 s[8:9], vcc
	s_cbranch_execz .LBB0_535
	s_bcnt1_i32_b64 s2, s[6:7]
	v_mov_b32_e32 v2, 0xbfa3000
	v_mov_b32_e32 v3, s2
	global_atomic_add v2, v2, v3, s[86:87] offset:1024 sc0

; DI unsigned xb_ld(unsigned* p) { return __hip_atomic_load(p, __ATOMIC_RELAXED, __HIP_MEMORY_SCOPE_AGENT); }
; DI unsigned xb_add(unsigned* p, unsigned v) { return __hip_atomic_fetch_add(p, v, __ATOMIC_RELAXED, __HIP_MEMORY_SCOPE_AGENT); }
; #define XB_SPIN(cond, bar) do { unsigned _sp = 0; while (cond) { __builtin_amdgcn_s_sleep(1); \
;     if ((++_sp & 255u) == 0u) { if (xb_ld(&(bar)[XB_TMO])) break; if (_sp > XB_SPIN_CAP) { atomicAdd(&(bar)[XB_TMO], 1u); break; } } } } while (0)
; DI void xcd_barrier(const XcdBarrier& b) {
;     ...
;       else XB_SPIN(xb_ld(&bar[XB_TOPGEN]) == tg, bar);
;       __builtin_amdgcn_fence(__ATOMIC_ACQUIRE, "agent");
;       xb_add(&bar[XB_XGEN(b.x)], 1u);
;       asm volatile("s_waitcnt vmcnt(0)" ::: "memory");
;     } else {
;       XB_SPIN(xb_ld(&bar[XB_XGEN(b.x)]) == gen, bar);
.LBB0_618:
	s_andn2_saveexec_b64 s[2:3], s[8:9]
	s_cbranch_execz .LBB0_638
	s_mov_b64 s[8:9], exec
	v_mov_b32_e32 v255, 0
	ds_read_b32 v255, v255 offset:264
	s_waitcnt lgkmcnt(0)
	v_cmp_ne_u32_e32 vcc, 0, v255
	s_cbranch_vccz .Lxl_full_4
	v_mov_b32_e32 v0, 0
	ds_read_b32 v0, v0 offset:260
.Lxl_spin_4:
	v_mov_b32_e32 v255, 0xbfa0208
	global_load_dword v255, v255, s[86:87] sc1
	s_waitcnt vmcnt(0) lgkmcnt(0)
	v_cmp_lt_u32_e32 vcc, v255, v0
	s_cbranch_vccz .Lxl_go_4
	s_sleep 1
	s_branch .Lxl_spin_4
.Lxl_go_4:
	s_branch .LBB0_635
.Lxl_full_4:
	buffer_wbl2 sc1
	s_waitcnt lgkmcnt(0)
	s_waitcnt vmcnt(0)
	v_mbcnt_lo_u32_b32 v0, s8, 0
	v_mbcnt_hi_u32_b32 v0, s9, v0
	v_cmp_eq_u32_e32 vcc, 0, v0
	s_and_saveexec_b64 s[10:11], vcc
	s_cbranch_execz .LBB0_621
	s_bcnt1_i32_b64 s2, s[8:9]
	v_mov_b32_e32 v2, 0xbfa3000
	v_mov_b32_e32 v3, s2
	global_atomic_add v2, v2, v3, s[86:87] offset:1024 sc0

; DI unsigned xb_ld(unsigned* p) { return __hip_atomic_load(p, __ATOMIC_RELAXED, __HIP_MEMORY_SCOPE_AGENT); }
; DI unsigned xb_add(unsigned* p, unsigned v) { return __hip_atomic_fetch_add(p, v, __ATOMIC_RELAXED, __HIP_MEMORY_SCOPE_AGENT); }
; #define XB_SPIN(cond, bar) do { unsigned _sp = 0; while (cond) { __builtin_amdgcn_s_sleep(1); \
;     if ((++_sp & 255u) == 0u) { if (xb_ld(&(bar)[XB_TMO])) break; if (_sp > XB_SPIN_CAP) { atomicAdd(&(bar)[XB_TMO], 1u); break; } } } } while (0)
; DI void xcd_barrier(const XcdBarrier& b) {
;     ...
;     if (old + 1u == (gen + 1u) * nloc) {
;       __builtin_amdgcn_fence(__ATOMIC_RELEASE, "agent");
;       asm volatile("s_waitcnt vmcnt(0)" ::: "memory");
;       const unsigned og = xb_add(&bar[XB_TOP], 1u);
;       const unsigned tg = og / nx;
;       if (og + 1u == (tg + 1u) * nx) xb_add(&bar[XB_TOPGEN], 1u);
;       else XB_SPIN(xb_ld(&bar[XB_TOPGEN]) == tg, bar);
.LBB0_1269:
	s_andn2_saveexec_b64 s[4:5], s[6:7]
	s_cbranch_execz .LBB0_1289
	s_mov_b64 s[6:7], exec
	v_mov_b32_e32 v255, 0
	ds_read_b32 v255, v255 offset:264
	s_waitcnt lgkmcnt(0)
	v_cmp_ne_u32_e32 vcc, 0, v255
	s_cbranch_vccz .Lxl_full_10
	v_mov_b32_e32 v255, 0xbfa020c
	v_mov_b32_e32 v0, 1
	global_atomic_add v255, v0, s[86:87]
	s_branch .LBB0_1286
.Lxl_full_10:
	buffer_wbl2 sc1
	s_waitcnt lgkmcnt(0)
	s_waitcnt vmcnt(0)
	v_mbcnt_lo_u32_b32 v0, s6, 0
	v_mbcnt_hi_u32_b32 v0, s7, v0
	v_cmp_eq_u32_e32 vcc, 0, v0
	s_and_saveexec_b64 s[8:9], vcc
	s_cbranch_execz .LBB0_1272
	s_bcnt1_i32_b64 s4, s[6:7]
	v_mov_b32_e32 v2, 0xbfa3000
	v_mov_b32_e32 v3, s4
	global_atomic_add v2, v2, v3, s[86:87] offset:1024 sc0

; DI unsigned xb_ld(unsigned* p) { return __hip_atomic_load(p, __ATOMIC_RELAXED, __HIP_MEMORY_SCOPE_AGENT); }
; DI unsigned xb_add(unsigned* p, unsigned v) { return __hip_atomic_fetch_add(p, v, __ATOMIC_RELAXED, __HIP_MEMORY_SCOPE_AGENT); }
; #define XB_SPIN(cond, bar) do { unsigned _sp = 0; while (cond) { __builtin_amdgcn_s_sleep(1); \
;     if ((++_sp & 255u) == 0u) { if (xb_ld(&(bar)[XB_TMO])) break; if (_sp > XB_SPIN_CAP) { atomicAdd(&(bar)[XB_TMO], 1u); break; } } } } while (0)
; DI void xcd_barrier(const XcdBarrier& b) {
;     ...
;       else XB_SPIN(xb_ld(&bar[XB_TOPGEN]) == tg, bar);
;       __builtin_amdgcn_fence(__ATOMIC_ACQUIRE, "agent");
;       xb_add(&bar[XB_XGEN(b.x)], 1u);
;       asm volatile("s_waitcnt vmcnt(0)" ::: "memory");
;     } else {
;       XB_SPIN(xb_ld(&bar[XB_XGEN(b.x)]) == gen, bar);
.LBB0_1355:
	s_andn2_saveexec_b64 s[4:5], s[6:7]
	s_cbranch_execz .LBB0_1375
	s_mov_b64 s[6:7], exec
	v_mov_b32_e32 v255, 0
	ds_read_b32 v255, v255 offset:264
	s_waitcnt lgkmcnt(0)
	v_cmp_ne_u32_e32 vcc, 0, v255
	s_cbranch_vccz .Lxl_full_11
	v_mov_b32_e32 v0, 0
	ds_read_b32 v0, v0 offset:260
.Lxl_spin_11:
	v_mov_b32_e32 v255, 0xbfa020c
	global_load_dword v255, v255, s[86:87] sc1
	s_waitcnt vmcnt(0) lgkmcnt(0)
	v_cmp_lt_u32_e32 vcc, v255, v0
	s_cbranch_vccz .Lxl_go_11
	s_sleep 1
	s_branch .Lxl_spin_11
